# LoRA-GEMM bf16 epilogue stores transposed across lanes (adjacent lanes write a row's 64 contiguous bytes), on top of v104
# baseline (speedup 1.0000x reference)
; __device__ __forceinline__ unsigned cvt_pk_bf16(float lo, float hi) { unsigned r; asm volatile("v_cvt_pk_bf16_f32 %0, %1, %2" : "=v"(r) : "v"(lo), "v"(hi)); return r; }
;   DI void operator()(const pg8::f32x4 (&acc)[2][2][4][2], const pg8::Unit& u, int wr, int wc, int fr, int fq) const {
;     const int row0 = u.pm * 256 + wr * 64 + fr, cl = wc * 32 + 8 * fq;
;     const int kind = u.pn;
;     bfr* base = RW + (size_t)kind * MR * 256;
;     const float osc = (kind < 2) ? 0.6065306597126334f : 1.f;
; #pragma unroll
;     for (int bj = 0; bj < 2; ++bj) {
;       const int c0 = cl + bj * 128;
;       float bias[8];
; #pragma unroll
;       for (int q = 0; q < 8; ++q) bias[q] = (kind < 2) ? w0[kind * 256 + c0 + q] : ((kind < 4) ? a0[(kind - 2) * 256 + c0 + q] : 0.f);
; #pragma unroll
;       for (int ai = 0; ai < 2; ++ai)
; #pragma unroll
;         for (int m = 0; m < 4; ++m) {
;           float o[8];
; #pragma unroll
;           for (int n = 0; n < 2; ++n)
; #pragma unroll
;             for (int e = 0; e < 4; ++e) {
;               const float x = acc[ai][bj][m][n][e] + bias[n * 4 + e];
;               const float sg = osc * __builtin_amdgcn_rcpf(1.f + __expf(-x));
;               o[n * 4 + e] = (kind < 4) ? sg : x;
;             }
;           u32x4 w; w.x = pg8::cvt_pk_bf16(o[0], o[1]); w.y = pg8::cvt_pk_bf16(o[2], o[3]); w.z = pg8::cvt_pk_bf16(o[4], o[5]); w.w = pg8::cvt_pk_bf16(o[6], o[7]);
;           *(u32x4*)(base + (size_t)(row0 + ai * 128 + m * 16) * 256 + c0) = w;
;         }
;     }
;   }
.LBB0_358:
	s_waitcnt vmcnt(0)
	v_add_f32_e32 v124, v124, v159
	v_mul_f32_e32 v143, 0xbfb8aa3b, v124
	v_exp_f32_e32 v143, v143
	v_mov_b32_e32 v140, 0x3f1b4598
	v_cndmask_b32_e64 v149, 1.0, v140, s[4:5]
	v_add_f32_e32 v125, v125, v157
	v_add_f32_e32 v143, 1.0, v143
	v_rcp_f32_e32 v143, v143
	v_add_f32_e32 v126, v126, v158
	v_add_f32_e32 v127, v127, v155
	v_add_f32_e32 v120, v120, v156
	v_mul_f32_e32 v143, v149, v143
	v_cndmask_b32_e64 v124, v124, v143, s[2:3]
	v_mul_f32_e32 v143, 0xbfb8aa3b, v125
	v_exp_f32_e32 v143, v143
	v_add_f32_e32 v121, v121, v151
	v_add_f32_e32 v122, v122, v154
	v_lshl_add_u32 v142, s46, 8, v144
	v_add_f32_e32 v143, 1.0, v143
	v_rcp_f32_e32 v143, v143
	v_mad_i64_i32 v[140:141], s[46:47], s45, v189, v[134:135]
	v_add_f32_e32 v116, v116, v159
	v_mul_f32_e32 v143, v149, v143
	v_cndmask_b32_e64 v125, v125, v143, s[2:3]
	v_mul_f32_e32 v143, 0xbfb8aa3b, v126
	v_exp_f32_e32 v143, v143
	v_add_f32_e32 v117, v117, v157
	v_add_f32_e32 v118, v118, v158
	v_add_f32_e32 v119, v119, v155
	v_add_f32_e32 v143, 1.0, v143
	v_rcp_f32_e32 v143, v143
	v_add_f32_e32 v112, v112, v156
	v_add_f32_e32 v113, v113, v151
	v_add_f32_e32 v114, v114, v154
	v_mul_f32_e32 v143, v149, v143
	v_cndmask_b32_e64 v126, v126, v143, s[2:3]
	v_mul_f32_e32 v143, 0xbfb8aa3b, v127
	v_exp_f32_e32 v143, v143
	v_add_f32_e32 v108, v108, v159
	v_add_f32_e32 v109, v109, v157
	v_add_f32_e32 v110, v110, v158
	v_add_f32_e32 v143, 1.0, v143
	v_rcp_f32_e32 v143, v143
	v_add_f32_e32 v111, v111, v155
	v_add_f32_e32 v104, v104, v156
	v_add_f32_e32 v105, v105, v151
	v_mul_f32_e32 v143, v149, v143
	v_cndmask_b32_e64 v127, v127, v143, s[2:3]
	v_mul_f32_e32 v143, 0xbfb8aa3b, v120
	v_exp_f32_e32 v143, v143
	v_add_f32_e32 v106, v106, v154
	v_add_f32_e32 v100, v100, v159
	v_add_f32_e32 v101, v101, v157
	v_add_f32_e32 v143, 1.0, v143
	v_rcp_f32_e32 v143, v143
	v_add_f32_e32 v102, v102, v158
	v_add_f32_e32 v103, v103, v155
	v_add_f32_e32 v96, v96, v156
	v_mul_f32_e32 v143, v149, v143
	v_cndmask_b32_e64 v120, v120, v143, s[2:3]
	v_mul_f32_e32 v143, 0xbfb8aa3b, v121
	v_exp_f32_e32 v143, v143
	v_add_f32_e32 v97, v97, v151
	v_add_f32_e32 v98, v98, v154
	v_add_f32_e32 v92, v92, v159
	v_add_f32_e32 v143, 1.0, v143
	v_rcp_f32_e32 v143, v143
	v_add_f32_e32 v93, v93, v157
	v_add_f32_e32 v94, v94, v158
	v_add_f32_e32 v95, v95, v155
	v_mul_f32_e32 v143, v149, v143
	v_cndmask_b32_e64 v121, v121, v143, s[2:3]
	v_mul_f32_e32 v143, 0xbfb8aa3b, v122
	v_exp_f32_e32 v143, v143
	v_add_f32_e32 v88, v88, v156
	s_mov_b32 s45, 0x10000
	v_add_f32_e32 v84, v84, v159
	v_add_f32_e32 v143, 1.0, v143
	v_rcp_f32_e32 v143, v143
	v_add_f32_e32 v85, v85, v157
	v_add_f32_e32 v86, v86, v158
	v_add_f32_e32 v87, v87, v155
	v_mul_f32_e32 v143, v149, v143
	v_cndmask_b32_e64 v143, v122, v143, s[2:3]
	v_add_f32_e32 v122, v123, v150
	v_mul_f32_e32 v123, 0xbfb8aa3b, v122
	v_exp_f32_e32 v123, v123
	v_add_f32_e32 v80, v80, v156
	v_add_f32_e32 v76, v76, v159
	v_add_f32_e32 v77, v77, v157
	v_add_f32_e32 v123, 1.0, v123
	v_rcp_f32_e32 v123, v123
	v_add_f32_e32 v78, v78, v158
	v_add_f32_e32 v79, v79, v155
	v_add_f32_e32 v72, v72, v156
	v_mul_f32_e32 v123, v149, v123
	v_cndmask_b32_e64 v160, v122, v123, s[2:3]
	v_cvt_pk_bf16_f32 v122, v124, v125
	v_cvt_pk_bf16_f32 v123, v126, v127
	v_cvt_pk_bf16_f32 v124, v120, v121
	v_cvt_pk_bf16_f32 v125, v143, v160
	v_ashrrev_i32_e32 v143, 31, v142
	v_lshlrev_b64 v[120:121], 9, v[142:143]
	v_lshl_add_u64 v[120:121], v[140:141], 0, v[120:121]
	v_and_b32_e32 v250, 63, v182
	v_lshrrev_b32_e32 v251, 2, v250
	v_and_b32_e32 v248, 3, v250
	v_lshlrev_b32_e32 v249, 4, v248
	v_lshl_add_u32 v248, v248, 4, v251
	v_lshlrev_b32_e32 v248, 2, v248
	v_lshl_add_u32 v249, v251, 9, v249
	v_and_b32_e32 v251, 15, v250
	v_lshrrev_b32_e32 v250, 4, v250
	v_lshlrev_b32_e32 v251, 9, v251
	v_lshl_add_u32 v251, v250, 4, v251
	v_sub_u32_e32 v249, v249, v251
	ds_bpermute_b32 v244, v248, v122
	ds_bpermute_b32 v245, v248, v123
	ds_bpermute_b32 v246, v248, v124
	ds_bpermute_b32 v247, v248, v125
	v_ashrrev_i32_e32 v251, 31, v249
	v_add_co_u32_e64 v250, s[98:99], v120, v249
	s_nop 1
	v_addc_co_u32_e64 v251, s[98:99], v121, v251, s[98:99]
	s_waitcnt lgkmcnt(0)
	global_store_dwordx4 v[250:251], v[244:247], off
	v_add_f32_e32 v68, v68, v159
	v_add_f32_e32 v69, v69, v157
	v_mul_f32_e32 v122, 0xbfb8aa3b, v116
	v_exp_f32_e32 v122, v122
	v_add_f32_e32 v70, v70, v158
	v_add_f32_e32 v71, v71, v155
	v_add_f32_e32 v64, v64, v156
	v_add_f32_e32 v122, 1.0, v122
	v_rcp_f32_e32 v122, v122
	s_nop 0
	v_mul_f32_e32 v122, v149, v122
	v_cndmask_b32_e64 v116, v116, v122, s[2:3]
	v_mul_f32_e32 v122, 0xbfb8aa3b, v117
	v_exp_f32_e32 v122, v122
	s_nop 0
	v_add_f32_e32 v122, 1.0, v122
	v_rcp_f32_e32 v122, v122
	s_nop 0
	v_mul_f32_e32 v122, v149, v122
	v_cndmask_b32_e64 v117, v117, v122, s[2:3]
	v_mul_f32_e32 v122, 0xbfb8aa3b, v118
	v_exp_f32_e32 v122, v122
	s_nop 0
	v_add_f32_e32 v122, 1.0, v122
	v_rcp_f32_e32 v122, v122
	s_nop 0
	v_mul_f32_e32 v122, v149, v122
	v_cndmask_b32_e64 v118, v118, v122, s[2:3]
	v_mul_f32_e32 v122, 0xbfb8aa3b, v119
	v_exp_f32_e32 v122, v122
	s_nop 0
	v_add_f32_e32 v122, 1.0, v122
	v_rcp_f32_e32 v122, v122
	s_nop 0
	v_mul_f32_e32 v122, v149, v122
	v_cndmask_b32_e64 v119, v119, v122, s[2:3]
	v_mul_f32_e32 v122, 0xbfb8aa3b, v112
	v_exp_f32_e32 v122, v122
	s_nop 0
	v_add_f32_e32 v122, 1.0, v122
	v_rcp_f32_e32 v122, v122
	s_nop 0
	v_mul_f32_e32 v122, v149, v122
	v_cndmask_b32_e64 v112, v112, v122, s[2:3]
	v_mul_f32_e32 v122, 0xbfb8aa3b, v113
	v_exp_f32_e32 v122, v122
	s_nop 0
	v_add_f32_e32 v122, 1.0, v122
	v_rcp_f32_e32 v122, v122
	s_nop 0
	v_mul_f32_e32 v122, v149, v122
	v_cndmask_b32_e64 v113, v113, v122, s[2:3]
; __device__ __forceinline__ unsigned cvt_pk_bf16(float lo, float hi) { unsigned r; asm volatile("v_cvt_pk_bf16_f32 %0, %1, %2" : "=v"(r) : "v"(lo), "v"(hi)); return r; }
;   DI void operator()(const pg8::f32x4 (&acc)[2][2][4][2], const pg8::Unit& u, int wr, int wc, int fr, int fq) const {
;     const int row0 = u.pm * 256 + wr * 64 + fr, cl = wc * 32 + 8 * fq;
;     const int kind = u.pn;
;     bfr* base = RW + (size_t)kind * MR * 256;
;     const float osc = (kind < 2) ? 0.6065306597126334f : 1.f;
; #pragma unroll
;     for (int bj = 0; bj < 2; ++bj) {
;       const int c0 = cl + bj * 128;
;       float bias[8];
; #pragma unroll
;       for (int q = 0; q < 8; ++q) bias[q] = (kind < 2) ? w0[kind * 256 + c0 + q] : ((kind < 4) ? a0[(kind - 2) * 256 + c0 + q] : 0.f);
; #pragma unroll
;       for (int ai = 0; ai < 2; ++ai)
; #pragma unroll
;         for (int m = 0; m < 4; ++m) {
;           float o[8];
; #pragma unroll
;           for (int n = 0; n < 2; ++n)
; #pragma unroll
;             for (int e = 0; e < 4; ++e) {
;               const float x = acc[ai][bj][m][n][e] + bias[n * 4 + e];
;               const float sg = osc * __builtin_amdgcn_rcpf(1.f + __expf(-x));
;               o[n * 4 + e] = (kind < 4) ? sg : x;
;             }
;           u32x4 w; w.x = pg8::cvt_pk_bf16(o[0], o[1]); w.y = pg8::cvt_pk_bf16(o[2], o[3]); w.z = pg8::cvt_pk_bf16(o[4], o[5]); w.w = pg8::cvt_pk_bf16(o[6], o[7]);
;           *(u32x4*)(base + (size_t)(row0 + ai * 128 + m * 16) * 256 + c0) = w;
;         }
;     }
;   }
	v_mul_f32_e32 v122, 0xbfb8aa3b, v114
	v_exp_f32_e32 v122, v122
	s_nop 0
	v_add_f32_e32 v122, 1.0, v122
	v_rcp_f32_e32 v122, v122
	s_nop 0
	v_mul_f32_e32 v122, v149, v122
	v_cndmask_b32_e64 v122, v114, v122, s[2:3]
	v_add_f32_e32 v114, v115, v150
	v_mul_f32_e32 v115, 0xbfb8aa3b, v114
	v_exp_f32_e32 v115, v115
	s_nop 0
	v_add_f32_e32 v115, 1.0, v115
	v_rcp_f32_e32 v115, v115
	s_nop 0
	v_mul_f32_e32 v115, v149, v115
	v_cndmask_b32_e64 v123, v114, v115, s[2:3]
	v_cvt_pk_bf16_f32 v114, v116, v117
	v_cvt_pk_bf16_f32 v115, v118, v119
	v_cvt_pk_bf16_f32 v116, v112, v113
	v_or_b32_e32 v112, 16, v142
	v_ashrrev_i32_e32 v113, 31, v112
	v_lshlrev_b64 v[112:113], 9, v[112:113]
	v_lshl_add_u64 v[112:113], v[140:141], 0, v[112:113]
	v_cvt_pk_bf16_f32 v117, v122, v123
	v_and_b32_e32 v250, 63, v182
	v_lshrrev_b32_e32 v251, 2, v250
	v_and_b32_e32 v248, 3, v250
	v_lshlrev_b32_e32 v249, 4, v248
	v_lshl_add_u32 v248, v248, 4, v251
	v_lshlrev_b32_e32 v248, 2, v248
	v_lshl_add_u32 v249, v251, 9, v249
	v_and_b32_e32 v251, 15, v250
	v_lshrrev_b32_e32 v250, 4, v250
	v_lshlrev_b32_e32 v251, 9, v251
	v_lshl_add_u32 v251, v250, 4, v251
	v_sub_u32_e32 v249, v249, v251
	ds_bpermute_b32 v244, v248, v114
	ds_bpermute_b32 v245, v248, v115
	ds_bpermute_b32 v246, v248, v116
	ds_bpermute_b32 v247, v248, v117
	v_ashrrev_i32_e32 v251, 31, v249
	v_add_co_u32_e64 v250, s[98:99], v112, v249
	s_nop 1
	v_addc_co_u32_e64 v251, s[98:99], v113, v251, s[98:99]
	s_waitcnt lgkmcnt(0)
	global_store_dwordx4 v[250:251], v[244:247], off
	s_nop 1
	v_mul_f32_e32 v114, 0xbfb8aa3b, v108
	v_exp_f32_e32 v114, v114
	s_nop 0
	v_add_f32_e32 v114, 1.0, v114
	v_rcp_f32_e32 v114, v114
	s_nop 0
	v_mul_f32_e32 v114, v149, v114
	v_cndmask_b32_e64 v108, v108, v114, s[2:3]
	v_mul_f32_e32 v114, 0xbfb8aa3b, v109
	v_exp_f32_e32 v114, v114
	s_nop 0
	v_add_f32_e32 v114, 1.0, v114
	v_rcp_f32_e32 v114, v114
	s_nop 0
	v_mul_f32_e32 v114, v149, v114
	v_cndmask_b32_e64 v109, v109, v114, s[2:3]
	v_mul_f32_e32 v114, 0xbfb8aa3b, v110
	v_exp_f32_e32 v114, v114
	s_nop 0
	v_add_f32_e32 v114, 1.0, v114
	v_rcp_f32_e32 v114, v114
	s_nop 0
	v_mul_f32_e32 v114, v149, v114
	v_cndmask_b32_e64 v110, v110, v114, s[2:3]
	v_mul_f32_e32 v114, 0xbfb8aa3b, v111
	v_exp_f32_e32 v114, v114
	s_nop 0
	v_add_f32_e32 v114, 1.0, v114
	v_rcp_f32_e32 v114, v114
	s_nop 0
	v_mul_f32_e32 v114, v149, v114
	v_cndmask_b32_e64 v111, v111, v114, s[2:3]
	v_mul_f32_e32 v114, 0xbfb8aa3b, v104
	v_exp_f32_e32 v114, v114
	s_nop 0
	v_add_f32_e32 v114, 1.0, v114
	v_rcp_f32_e32 v114, v114
	s_nop 0
	v_mul_f32_e32 v114, v149, v114
	v_cndmask_b32_e64 v104, v104, v114, s[2:3]
	v_mul_f32_e32 v114, 0xbfb8aa3b, v105
	v_exp_f32_e32 v114, v114
	s_nop 0
	v_add_f32_e32 v114, 1.0, v114
	v_rcp_f32_e32 v114, v114
	s_nop 0
	v_mul_f32_e32 v114, v149, v114
	v_cndmask_b32_e64 v105, v105, v114, s[2:3]
	v_mul_f32_e32 v114, 0xbfb8aa3b, v106
	v_exp_f32_e32 v114, v114
	s_nop 0
	v_add_f32_e32 v114, 1.0, v114
	v_rcp_f32_e32 v114, v114
	s_nop 0
	v_mul_f32_e32 v114, v149, v114
	v_cndmask_b32_e64 v114, v106, v114, s[2:3]
	v_add_f32_e32 v106, v107, v150
	v_mul_f32_e32 v107, 0xbfb8aa3b, v106
	v_exp_f32_e32 v107, v107
	s_nop 0
	v_add_f32_e32 v107, 1.0, v107
	v_rcp_f32_e32 v107, v107
	s_nop 0
	v_mul_f32_e32 v107, v149, v107
	v_cndmask_b32_e64 v115, v106, v107, s[2:3]
	v_cvt_pk_bf16_f32 v106, v108, v109
	v_cvt_pk_bf16_f32 v107, v110, v111
	v_cvt_pk_bf16_f32 v108, v104, v105
	v_or_b32_e32 v104, 32, v142
	v_ashrrev_i32_e32 v105, 31, v104
	v_lshlrev_b64 v[104:105], 9, v[104:105]
	v_lshl_add_u64 v[104:105], v[140:141], 0, v[104:105]
	v_cvt_pk_bf16_f32 v109, v114, v115
	v_and_b32_e32 v250, 63, v182
	v_lshrrev_b32_e32 v251, 2, v250
	v_and_b32_e32 v248, 3, v250
	v_lshlrev_b32_e32 v249, 4, v248
	v_lshl_add_u32 v248, v248, 4, v251
	v_lshlrev_b32_e32 v248, 2, v248
	v_lshl_add_u32 v249, v251, 9, v249
	v_and_b32_e32 v251, 15, v250
	v_lshrrev_b32_e32 v250, 4, v250
	v_lshlrev_b32_e32 v251, 9, v251
	v_lshl_add_u32 v251, v250, 4, v251
	v_sub_u32_e32 v249, v249, v251
	ds_bpermute_b32 v244, v248, v106
	ds_bpermute_b32 v245, v248, v107
	ds_bpermute_b32 v246, v248, v108
	ds_bpermute_b32 v247, v248, v109
	v_ashrrev_i32_e32 v251, 31, v249
	v_add_co_u32_e64 v250, s[98:99], v104, v249
	s_nop 1
	v_addc_co_u32_e64 v251, s[98:99], v105, v251, s[98:99]
	s_waitcnt lgkmcnt(0)
; __device__ __forceinline__ unsigned cvt_pk_bf16(float lo, float hi) { unsigned r; asm volatile("v_cvt_pk_bf16_f32 %0, %1, %2" : "=v"(r) : "v"(lo), "v"(hi)); return r; }
;   DI void operator()(const pg8::f32x4 (&acc)[2][2][4][2], const pg8::Unit& u, int wr, int wc, int fr, int fq) const {
;     const int row0 = u.pm * 256 + wr * 64 + fr, cl = wc * 32 + 8 * fq;
;     const int kind = u.pn;
;     bfr* base = RW + (size_t)kind * MR * 256;
;     const float osc = (kind < 2) ? 0.6065306597126334f : 1.f;
; #pragma unroll
;     for (int bj = 0; bj < 2; ++bj) {
;       const int c0 = cl + bj * 128;
;       float bias[8];
; #pragma unroll
;       for (int q = 0; q < 8; ++q) bias[q] = (kind < 2) ? w0[kind * 256 + c0 + q] : ((kind < 4) ? a0[(kind - 2) * 256 + c0 + q] : 0.f);
; #pragma unroll
;       for (int ai = 0; ai < 2; ++ai)
; #pragma unroll
;         for (int m = 0; m < 4; ++m) {
;           float o[8];
; #pragma unroll
;           for (int n = 0; n < 2; ++n)
; #pragma unroll
;             for (int e = 0; e < 4; ++e) {
;               const float x = acc[ai][bj][m][n][e] + bias[n * 4 + e];
;               const float sg = osc * __builtin_amdgcn_rcpf(1.f + __expf(-x));
;               o[n * 4 + e] = (kind < 4) ? sg : x;
;             }
;           u32x4 w; w.x = pg8::cvt_pk_bf16(o[0], o[1]); w.y = pg8::cvt_pk_bf16(o[2], o[3]); w.z = pg8::cvt_pk_bf16(o[4], o[5]); w.w = pg8::cvt_pk_bf16(o[6], o[7]);
;           *(u32x4*)(base + (size_t)(row0 + ai * 128 + m * 16) * 256 + c0) = w;
;         }
;     }
;   }
	global_store_dwordx4 v[250:251], v[244:247], off
	s_nop 1
	v_mul_f32_e32 v106, 0xbfb8aa3b, v100
	v_exp_f32_e32 v106, v106
	s_nop 0
	v_add_f32_e32 v106, 1.0, v106
	v_rcp_f32_e32 v106, v106
	s_nop 0
	v_mul_f32_e32 v106, v149, v106
	v_cndmask_b32_e64 v100, v100, v106, s[2:3]
	v_mul_f32_e32 v106, 0xbfb8aa3b, v101
	v_exp_f32_e32 v106, v106
	s_nop 0
	v_add_f32_e32 v106, 1.0, v106
	v_rcp_f32_e32 v106, v106
	s_nop 0
	v_mul_f32_e32 v106, v149, v106
	v_cndmask_b32_e64 v101, v101, v106, s[2:3]
	v_mul_f32_e32 v106, 0xbfb8aa3b, v102
	v_exp_f32_e32 v106, v106
	s_nop 0
	v_add_f32_e32 v106, 1.0, v106
	v_rcp_f32_e32 v106, v106
	s_nop 0
	v_mul_f32_e32 v106, v149, v106
	v_cndmask_b32_e64 v102, v102, v106, s[2:3]
	v_mul_f32_e32 v106, 0xbfb8aa3b, v103
	v_exp_f32_e32 v106, v106
	s_nop 0
	v_add_f32_e32 v106, 1.0, v106
	v_rcp_f32_e32 v106, v106
	s_nop 0
	v_mul_f32_e32 v106, v149, v106
	v_cndmask_b32_e64 v103, v103, v106, s[2:3]
	v_mul_f32_e32 v106, 0xbfb8aa3b, v96
	v_exp_f32_e32 v106, v106
	s_nop 0
	v_add_f32_e32 v106, 1.0, v106
	v_rcp_f32_e32 v106, v106
	s_nop 0
	v_mul_f32_e32 v106, v149, v106
	v_cndmask_b32_e64 v96, v96, v106, s[2:3]
	v_mul_f32_e32 v106, 0xbfb8aa3b, v97
	v_exp_f32_e32 v106, v106
	s_nop 0
	v_add_f32_e32 v106, 1.0, v106
	v_rcp_f32_e32 v106, v106
	s_nop 0
	v_mul_f32_e32 v106, v149, v106
	v_cndmask_b32_e64 v97, v97, v106, s[2:3]
	v_mul_f32_e32 v106, 0xbfb8aa3b, v98
	v_exp_f32_e32 v106, v106
	s_nop 0
	v_add_f32_e32 v106, 1.0, v106
	v_rcp_f32_e32 v106, v106
	s_nop 0
	v_mul_f32_e32 v106, v149, v106
	v_cndmask_b32_e64 v106, v98, v106, s[2:3]
	v_add_f32_e32 v98, v99, v150
	v_mul_f32_e32 v99, 0xbfb8aa3b, v98
	v_exp_f32_e32 v99, v99
	s_nop 0
	v_add_f32_e32 v99, 1.0, v99
	v_rcp_f32_e32 v99, v99
	s_nop 0
	v_mul_f32_e32 v99, v149, v99
	v_cndmask_b32_e64 v107, v98, v99, s[2:3]
	v_cvt_pk_bf16_f32 v98, v100, v101
	v_cvt_pk_bf16_f32 v99, v102, v103
	v_cvt_pk_bf16_f32 v100, v96, v97
	v_or_b32_e32 v96, 48, v142
	v_ashrrev_i32_e32 v97, 31, v96
	v_lshlrev_b64 v[96:97], 9, v[96:97]
	v_lshl_add_u64 v[96:97], v[140:141], 0, v[96:97]
	v_cvt_pk_bf16_f32 v101, v106, v107
	v_and_b32_e32 v250, 63, v182
	v_lshrrev_b32_e32 v251, 2, v250
	v_and_b32_e32 v248, 3, v250
	v_lshlrev_b32_e32 v249, 4, v248
	v_lshl_add_u32 v248, v248, 4, v251
	v_lshlrev_b32_e32 v248, 2, v248
	v_lshl_add_u32 v249, v251, 9, v249
	v_and_b32_e32 v251, 15, v250
	v_lshrrev_b32_e32 v250, 4, v250
	v_lshlrev_b32_e32 v251, 9, v251
	v_lshl_add_u32 v251, v250, 4, v251
	v_sub_u32_e32 v249, v249, v251
	ds_bpermute_b32 v244, v248, v98
	ds_bpermute_b32 v245, v248, v99
	ds_bpermute_b32 v246, v248, v100
	ds_bpermute_b32 v247, v248, v101
	v_ashrrev_i32_e32 v251, 31, v249
	v_add_co_u32_e64 v250, s[98:99], v96, v249
	s_nop 1
	v_addc_co_u32_e64 v251, s[98:99], v97, v251, s[98:99]
	s_waitcnt lgkmcnt(0)
	global_store_dwordx4 v[250:251], v[244:247], off
	s_nop 1
	v_mul_f32_e32 v98, 0xbfb8aa3b, v92
	v_exp_f32_e32 v98, v98
	s_nop 0
	v_add_f32_e32 v98, 1.0, v98
	v_rcp_f32_e32 v98, v98
	s_nop 0
	v_mul_f32_e32 v98, v149, v98
	v_cndmask_b32_e64 v92, v92, v98, s[2:3]
	v_mul_f32_e32 v98, 0xbfb8aa3b, v93
	v_exp_f32_e32 v98, v98
	s_nop 0
	v_add_f32_e32 v98, 1.0, v98
	v_rcp_f32_e32 v98, v98
	s_nop 0
	v_mul_f32_e32 v98, v149, v98
	v_cndmask_b32_e64 v93, v93, v98, s[2:3]
	v_mul_f32_e32 v98, 0xbfb8aa3b, v94
	v_exp_f32_e32 v98, v98
	s_nop 0
	v_add_f32_e32 v98, 1.0, v98
	v_rcp_f32_e32 v98, v98
	s_nop 0
	v_mul_f32_e32 v98, v149, v98
	v_cndmask_b32_e64 v94, v94, v98, s[2:3]
	v_mul_f32_e32 v98, 0xbfb8aa3b, v95
	v_exp_f32_e32 v98, v98
	s_nop 0
	v_add_f32_e32 v98, 1.0, v98
	v_rcp_f32_e32 v98, v98
	s_nop 0
	v_mul_f32_e32 v98, v149, v98
	v_cndmask_b32_e64 v95, v95, v98, s[2:3]
	v_mul_f32_e32 v98, 0xbfb8aa3b, v88
	v_exp_f32_e32 v98, v98
	s_nop 0
	v_add_f32_e32 v98, 1.0, v98
	v_rcp_f32_e32 v98, v98
	s_nop 0
	v_mul_f32_e32 v98, v149, v98
	v_cndmask_b32_e64 v98, v88, v98, s[2:3]
	v_add_f32_e32 v88, v89, v151
	v_mul_f32_e32 v89, 0xbfb8aa3b, v88
	v_exp_f32_e32 v89, v89
	s_nop 0
	v_add_f32_e32 v89, 1.0, v89
	v_rcp_f32_e32 v89, v89
	s_nop 0
	v_mul_f32_e32 v89, v149, v89
	v_cndmask_b32_e64 v99, v88, v89, s[2:3]
	v_add_f32_e32 v88, v90, v154
	v_mul_f32_e32 v89, 0xbfb8aa3b, v88
	v_exp_f32_e32 v89, v89
	s_nop 0
	v_add_f32_e32 v89, 1.0, v89
	v_rcp_f32_e32 v89, v89
	s_nop 0
	v_mul_f32_e32 v89, v149, v89
	v_cndmask_b32_e64 v100, v88, v89, s[2:3]
	v_add_f32_e32 v88, v91, v150
	v_mul_f32_e32 v89, 0xbfb8aa3b, v88
	v_exp_f32_e32 v89, v89
	s_nop 0
	v_add_f32_e32 v89, 1.0, v89
	v_rcp_f32_e32 v89, v89
	s_nop 0
	v_mul_f32_e32 v89, v149, v89
	v_cndmask_b32_e64 v91, v88, v89, s[2:3]
	v_cvt_pk_bf16_f32 v88, v92, v93
	v_add_co_u32_e32 v92, vcc, s45, v120
	v_cvt_pk_bf16_f32 v89, v94, v95
	v_cvt_pk_bf16_f32 v90, v98, v99
	v_cvt_pk_bf16_f32 v91, v100, v91
	s_mov_b32 s45, 0x12000
	s_nop 0
	v_addc_co_u32_e32 v93, vcc, 0, v121, vcc
	v_and_b32_e32 v250, 63, v182
	v_lshrrev_b32_e32 v251, 2, v250
	v_and_b32_e32 v248, 3, v250
	v_lshlrev_b32_e32 v249, 4, v248
	v_lshl_add_u32 v248, v248, 4, v251
	v_lshlrev_b32_e32 v248, 2, v248
	v_lshl_add_u32 v249, v251, 9, v249
	v_and_b32_e32 v251, 15, v250
	v_lshrrev_b32_e32 v250, 4, v250
	v_lshlrev_b32_e32 v251, 9, v251
	v_lshl_add_u32 v251, v250, 4, v251
	v_sub_u32_e32 v249, v249, v251
	ds_bpermute_b32 v244, v248, v88
	ds_bpermute_b32 v245, v248, v89
	ds_bpermute_b32 v246, v248, v90
	ds_bpermute_b32 v247, v248, v91
	v_ashrrev_i32_e32 v251, 31, v249
	v_add_co_u32_e64 v250, s[98:99], v92, v249
	s_nop 1
	v_addc_co_u32_e64 v251, s[98:99], v93, v251, s[98:99]
	s_waitcnt lgkmcnt(0)
; __device__ __forceinline__ unsigned cvt_pk_bf16(float lo, float hi) { unsigned r; asm volatile("v_cvt_pk_bf16_f32 %0, %1, %2" : "=v"(r) : "v"(lo), "v"(hi)); return r; }
;   DI void operator()(const pg8::f32x4 (&acc)[2][2][4][2], const pg8::Unit& u, int wr, int wc, int fr, int fq) const {
;     const int row0 = u.pm * 256 + wr * 64 + fr, cl = wc * 32 + 8 * fq;
;     const int kind = u.pn;
;     bfr* base = RW + (size_t)kind * MR * 256;
;     const float osc = (kind < 2) ? 0.6065306597126334f : 1.f;
; #pragma unroll
;     for (int bj = 0; bj < 2; ++bj) {
;       const int c0 = cl + bj * 128;
;       float bias[8];
; #pragma unroll
;       for (int q = 0; q < 8; ++q) bias[q] = (kind < 2) ? w0[kind * 256 + c0 + q] : ((kind < 4) ? a0[(kind - 2) * 256 + c0 + q] : 0.f);
; #pragma unroll
;       for (int ai = 0; ai < 2; ++ai)
; #pragma unroll
;         for (int m = 0; m < 4; ++m) {
;           float o[8];
; #pragma unroll
;           for (int n = 0; n < 2; ++n)
; #pragma unroll
;             for (int e = 0; e < 4; ++e) {
;               const float x = acc[ai][bj][m][n][e] + bias[n * 4 + e];
;               const float sg = osc * __builtin_amdgcn_rcpf(1.f + __expf(-x));
;               o[n * 4 + e] = (kind < 4) ? sg : x;
;             }
;           u32x4 w; w.x = pg8::cvt_pk_bf16(o[0], o[1]); w.y = pg8::cvt_pk_bf16(o[2], o[3]); w.z = pg8::cvt_pk_bf16(o[4], o[5]); w.w = pg8::cvt_pk_bf16(o[6], o[7]);
;           *(u32x4*)(base + (size_t)(row0 + ai * 128 + m * 16) * 256 + c0) = w;
;         }
;     }
;   }
	global_store_dwordx4 v[250:251], v[244:247], off
	s_nop 1
	v_mul_f32_e32 v88, 0xbfb8aa3b, v84
	v_exp_f32_e32 v88, v88
	s_nop 0
	v_add_f32_e32 v88, 1.0, v88
	v_rcp_f32_e32 v88, v88
	s_nop 0
	v_mul_f32_e32 v88, v149, v88
	v_cndmask_b32_e64 v84, v84, v88, s[2:3]
	v_mul_f32_e32 v88, 0xbfb8aa3b, v85
	v_exp_f32_e32 v88, v88
	s_nop 0
	v_add_f32_e32 v88, 1.0, v88
	v_rcp_f32_e32 v88, v88
	s_nop 0
	v_mul_f32_e32 v88, v149, v88
	v_cndmask_b32_e64 v85, v85, v88, s[2:3]
	v_mul_f32_e32 v88, 0xbfb8aa3b, v86
	v_exp_f32_e32 v88, v88
	s_nop 0
	v_add_f32_e32 v88, 1.0, v88
	v_rcp_f32_e32 v88, v88
	s_nop 0
	v_mul_f32_e32 v88, v149, v88
	v_cndmask_b32_e64 v86, v86, v88, s[2:3]
	v_mul_f32_e32 v88, 0xbfb8aa3b, v87
	v_exp_f32_e32 v88, v88
	s_nop 0
	v_add_f32_e32 v88, 1.0, v88
	v_rcp_f32_e32 v88, v88
	s_nop 0
	v_mul_f32_e32 v88, v149, v88
	v_cndmask_b32_e64 v87, v87, v88, s[2:3]
	v_mul_f32_e32 v88, 0xbfb8aa3b, v80
	v_exp_f32_e32 v88, v88
	s_nop 0
	v_add_f32_e32 v88, 1.0, v88
	v_rcp_f32_e32 v88, v88
	s_nop 0
	v_mul_f32_e32 v88, v149, v88
	v_cndmask_b32_e64 v88, v80, v88, s[2:3]
	v_add_f32_e32 v80, v81, v151
	v_mul_f32_e32 v81, 0xbfb8aa3b, v80
	v_exp_f32_e32 v81, v81
	s_nop 0
	v_add_f32_e32 v81, 1.0, v81
	v_rcp_f32_e32 v81, v81
	s_nop 0
	v_mul_f32_e32 v81, v149, v81
	v_cndmask_b32_e64 v89, v80, v81, s[2:3]
	v_add_f32_e32 v80, v82, v154
	v_mul_f32_e32 v81, 0xbfb8aa3b, v80
	v_exp_f32_e32 v81, v81
	s_nop 0
	v_add_f32_e32 v81, 1.0, v81
	v_rcp_f32_e32 v81, v81
	s_nop 0
	v_mul_f32_e32 v81, v149, v81
	v_cndmask_b32_e64 v90, v80, v81, s[2:3]
	v_add_f32_e32 v80, v83, v150
	v_mul_f32_e32 v81, 0xbfb8aa3b, v80
	v_exp_f32_e32 v81, v81
	s_nop 0
	v_add_f32_e32 v81, 1.0, v81
	v_rcp_f32_e32 v81, v81
	s_nop 0
	v_mul_f32_e32 v81, v149, v81
	v_cndmask_b32_e64 v83, v80, v81, s[2:3]
	v_cvt_pk_bf16_f32 v80, v84, v85
	v_add_co_u32_e32 v84, vcc, s45, v120
	v_cvt_pk_bf16_f32 v81, v86, v87
	v_cvt_pk_bf16_f32 v82, v88, v89
	v_cvt_pk_bf16_f32 v83, v90, v83
	s_mov_b32 s45, 0x14000
	s_nop 0
	v_addc_co_u32_e32 v85, vcc, 0, v121, vcc
	v_and_b32_e32 v250, 63, v182
	v_lshrrev_b32_e32 v251, 2, v250
	v_and_b32_e32 v248, 3, v250
	v_lshlrev_b32_e32 v249, 4, v248
	v_lshl_add_u32 v248, v248, 4, v251
	v_lshlrev_b32_e32 v248, 2, v248
	v_lshl_add_u32 v249, v251, 9, v249
	v_and_b32_e32 v251, 15, v250
	v_lshrrev_b32_e32 v250, 4, v250
	v_lshlrev_b32_e32 v251, 9, v251
	v_lshl_add_u32 v251, v250, 4, v251
	v_sub_u32_e32 v249, v249, v251
	ds_bpermute_b32 v244, v248, v80
	ds_bpermute_b32 v245, v248, v81
	ds_bpermute_b32 v246, v248, v82
	ds_bpermute_b32 v247, v248, v83
	v_ashrrev_i32_e32 v251, 31, v249
	v_add_co_u32_e64 v250, s[98:99], v84, v249
	s_nop 1
	v_addc_co_u32_e64 v251, s[98:99], v85, v251, s[98:99]
	s_waitcnt lgkmcnt(0)
	global_store_dwordx4 v[250:251], v[244:247], off
	s_nop 1
	v_mul_f32_e32 v80, 0xbfb8aa3b, v76
	v_exp_f32_e32 v80, v80
	s_nop 0
	v_add_f32_e32 v80, 1.0, v80
	v_rcp_f32_e32 v80, v80
	s_nop 0
	v_mul_f32_e32 v80, v149, v80
	v_cndmask_b32_e64 v76, v76, v80, s[2:3]
	v_mul_f32_e32 v80, 0xbfb8aa3b, v77
	v_exp_f32_e32 v80, v80
	s_nop 0
	v_add_f32_e32 v80, 1.0, v80
	v_rcp_f32_e32 v80, v80
	s_nop 0
	v_mul_f32_e32 v80, v149, v80
	v_cndmask_b32_e64 v77, v77, v80, s[2:3]
	v_mul_f32_e32 v80, 0xbfb8aa3b, v78
	v_exp_f32_e32 v80, v80
	s_nop 0
	v_add_f32_e32 v80, 1.0, v80
	v_rcp_f32_e32 v80, v80
	s_nop 0
	v_mul_f32_e32 v80, v149, v80
	v_cndmask_b32_e64 v78, v78, v80, s[2:3]
	v_mul_f32_e32 v80, 0xbfb8aa3b, v79
	v_exp_f32_e32 v80, v80
	s_nop 0
	v_add_f32_e32 v80, 1.0, v80
	v_rcp_f32_e32 v80, v80
	s_nop 0
	v_mul_f32_e32 v80, v149, v80
	v_cndmask_b32_e64 v79, v79, v80, s[2:3]
	v_mul_f32_e32 v80, 0xbfb8aa3b, v72
	v_exp_f32_e32 v80, v80
	s_nop 0
	v_add_f32_e32 v80, 1.0, v80
	v_rcp_f32_e32 v80, v80
	s_nop 0
	v_mul_f32_e32 v80, v149, v80
	v_cndmask_b32_e64 v80, v72, v80, s[2:3]
	v_add_f32_e32 v72, v73, v151
	v_mul_f32_e32 v73, 0xbfb8aa3b, v72
	v_exp_f32_e32 v73, v73
	s_nop 0
	v_add_f32_e32 v73, 1.0, v73
	v_rcp_f32_e32 v73, v73
	s_nop 0
	v_mul_f32_e32 v73, v149, v73
	v_cndmask_b32_e64 v81, v72, v73, s[2:3]
	v_add_f32_e32 v72, v74, v154
	v_mul_f32_e32 v73, 0xbfb8aa3b, v72
	v_exp_f32_e32 v73, v73
	s_nop 0
	v_add_f32_e32 v73, 1.0, v73
	v_rcp_f32_e32 v73, v73
	s_nop 0
	v_mul_f32_e32 v73, v149, v73
	v_cndmask_b32_e64 v82, v72, v73, s[2:3]
	v_add_f32_e32 v72, v75, v150
	v_mul_f32_e32 v73, 0xbfb8aa3b, v72
	v_exp_f32_e32 v73, v73
	s_nop 0
	v_add_f32_e32 v73, 1.0, v73
	v_rcp_f32_e32 v73, v73
	s_nop 0
	v_mul_f32_e32 v73, v149, v73
	v_cndmask_b32_e64 v75, v72, v73, s[2:3]
	v_cvt_pk_bf16_f32 v72, v76, v77
	v_add_co_u32_e32 v76, vcc, s45, v120
	v_cvt_pk_bf16_f32 v73, v78, v79
	v_cvt_pk_bf16_f32 v74, v80, v81
	v_cvt_pk_bf16_f32 v75, v82, v75
	v_mov_b32_e32 v79, 0
	s_nop 0
	v_addc_co_u32_e32 v77, vcc, 0, v121, vcc
	v_and_b32_e32 v250, 63, v182
	v_lshrrev_b32_e32 v251, 2, v250
	v_and_b32_e32 v248, 3, v250
	v_lshlrev_b32_e32 v249, 4, v248
	v_lshl_add_u32 v248, v248, 4, v251
	v_lshlrev_b32_e32 v248, 2, v248
	v_lshl_add_u32 v249, v251, 9, v249
	v_and_b32_e32 v251, 15, v250
	v_lshrrev_b32_e32 v250, 4, v250
	v_lshlrev_b32_e32 v251, 9, v251
	v_lshl_add_u32 v251, v250, 4, v251
	v_sub_u32_e32 v249, v249, v251
	ds_bpermute_b32 v244, v248, v72
	ds_bpermute_b32 v245, v248, v73
	ds_bpermute_b32 v246, v248, v74
	ds_bpermute_b32 v247, v248, v75
	v_ashrrev_i32_e32 v251, 31, v249
	v_add_co_u32_e64 v250, s[98:99], v76, v249
	s_nop 1
	v_addc_co_u32_e64 v251, s[98:99], v77, v251, s[98:99]
	s_waitcnt lgkmcnt(0)
; __device__ __forceinline__ unsigned cvt_pk_bf16(float lo, float hi) { unsigned r; asm volatile("v_cvt_pk_bf16_f32 %0, %1, %2" : "=v"(r) : "v"(lo), "v"(hi)); return r; }
;   DI void operator()(const pg8::f32x4 (&acc)[2][2][4][2], const pg8::Unit& u, int wr, int wc, int fr, int fq) const {
;     const int row0 = u.pm * 256 + wr * 64 + fr, cl = wc * 32 + 8 * fq;
;     const int kind = u.pn;
;     bfr* base = RW + (size_t)kind * MR * 256;
;     const float osc = (kind < 2) ? 0.6065306597126334f : 1.f;
; #pragma unroll
;     for (int bj = 0; bj < 2; ++bj) {
;       const int c0 = cl + bj * 128;
;       float bias[8];
; #pragma unroll
;       for (int q = 0; q < 8; ++q) bias[q] = (kind < 2) ? w0[kind * 256 + c0 + q] : ((kind < 4) ? a0[(kind - 2) * 256 + c0 + q] : 0.f);
; #pragma unroll
;       for (int ai = 0; ai < 2; ++ai)
; #pragma unroll
;         for (int m = 0; m < 4; ++m) {
;           float o[8];
; #pragma unroll
;           for (int n = 0; n < 2; ++n)
; #pragma unroll
;             for (int e = 0; e < 4; ++e) {
;               const float x = acc[ai][bj][m][n][e] + bias[n * 4 + e];
;               const float sg = osc * __builtin_amdgcn_rcpf(1.f + __expf(-x));
;               o[n * 4 + e] = (kind < 4) ? sg : x;
;             }
;           u32x4 w; w.x = pg8::cvt_pk_bf16(o[0], o[1]); w.y = pg8::cvt_pk_bf16(o[2], o[3]); w.z = pg8::cvt_pk_bf16(o[4], o[5]); w.w = pg8::cvt_pk_bf16(o[6], o[7]);
;           *(u32x4*)(base + (size_t)(row0 + ai * 128 + m * 16) * 256 + c0) = w;
;         }
;     }
;   }
	global_store_dwordx4 v[250:251], v[244:247], off
	v_mov_b32_e32 v77, 0
	s_nop 0
	v_mul_f32_e32 v72, 0xbfb8aa3b, v68
	v_exp_f32_e32 v72, v72
	s_nop 0
	v_add_f32_e32 v72, 1.0, v72
	v_rcp_f32_e32 v72, v72
	s_nop 0
	v_mul_f32_e32 v72, v149, v72
	v_cndmask_b32_e64 v68, v68, v72, s[2:3]
	v_mul_f32_e32 v72, 0xbfb8aa3b, v69
	v_exp_f32_e32 v72, v72
	s_nop 0
	v_add_f32_e32 v72, 1.0, v72
	v_rcp_f32_e32 v72, v72
	s_nop 0
	v_mul_f32_e32 v72, v149, v72
	v_cndmask_b32_e64 v69, v69, v72, s[2:3]
	v_mul_f32_e32 v72, 0xbfb8aa3b, v70
	v_exp_f32_e32 v72, v72
	s_nop 0
	v_add_f32_e32 v72, 1.0, v72
	v_rcp_f32_e32 v72, v72
	s_nop 0
	v_mul_f32_e32 v72, v149, v72
	v_cndmask_b32_e64 v70, v70, v72, s[2:3]
	v_mul_f32_e32 v72, 0xbfb8aa3b, v71
	v_exp_f32_e32 v72, v72
	s_nop 0
	v_add_f32_e32 v72, 1.0, v72
	v_rcp_f32_e32 v72, v72
	s_nop 0
	v_mul_f32_e32 v72, v149, v72
	v_cndmask_b32_e64 v71, v71, v72, s[2:3]
	v_mul_f32_e32 v72, 0xbfb8aa3b, v64
	v_exp_f32_e32 v72, v72
	s_nop 0
	v_add_f32_e32 v72, 1.0, v72
	v_rcp_f32_e32 v72, v72
	s_nop 0
	v_mul_f32_e32 v72, v149, v72
	v_cndmask_b32_e64 v72, v64, v72, s[2:3]
	v_add_f32_e32 v64, v65, v151
	v_mul_f32_e32 v65, 0xbfb8aa3b, v64
	v_exp_f32_e32 v65, v65
	s_nop 0
	v_add_f32_e32 v65, 1.0, v65
	v_rcp_f32_e32 v65, v65
	s_nop 0
	v_mul_f32_e32 v65, v149, v65
	v_cndmask_b32_e64 v73, v64, v65, s[2:3]
	v_add_f32_e32 v64, v66, v154
	v_mul_f32_e32 v65, 0xbfb8aa3b, v64
	v_exp_f32_e32 v65, v65
	s_nop 0
	v_add_f32_e32 v65, 1.0, v65
	v_rcp_f32_e32 v65, v65
	s_nop 0
	v_mul_f32_e32 v65, v149, v65
	v_cndmask_b32_e64 v74, v64, v65, s[2:3]
	v_add_f32_e32 v64, v67, v150
	v_mul_f32_e32 v65, 0xbfb8aa3b, v64
	v_exp_f32_e32 v65, v65
	s_nop 0
	v_add_f32_e32 v65, 1.0, v65
	v_rcp_f32_e32 v65, v65
	s_nop 0
	v_mul_f32_e32 v65, v149, v65
	v_cndmask_b32_e64 v67, v64, v65, s[2:3]
	v_cvt_pk_bf16_f32 v64, v68, v69
	v_add_co_u32_e32 v68, vcc, 0x16000, v120
	v_cvt_pk_bf16_f32 v65, v70, v71
	v_cvt_pk_bf16_f32 v66, v72, v73
	v_cvt_pk_bf16_f32 v67, v74, v67
	s_nop 1
	v_addc_co_u32_e32 v69, vcc, 0, v121, vcc
	v_and_b32_e32 v250, 63, v182
	v_lshrrev_b32_e32 v251, 2, v250
	v_and_b32_e32 v248, 3, v250
	v_lshlrev_b32_e32 v249, 4, v248
	v_lshl_add_u32 v248, v248, 4, v251
	v_lshlrev_b32_e32 v248, 2, v248
	v_lshl_add_u32 v249, v251, 9, v249
	v_and_b32_e32 v251, 15, v250
	v_lshrrev_b32_e32 v250, 4, v250
	v_lshlrev_b32_e32 v251, 9, v251
	v_lshl_add_u32 v251, v250, 4, v251
	v_sub_u32_e32 v249, v249, v251
	ds_bpermute_b32 v244, v248, v64
	ds_bpermute_b32 v245, v248, v65
	ds_bpermute_b32 v246, v248, v66
	ds_bpermute_b32 v247, v248, v67
	v_ashrrev_i32_e32 v251, 31, v249
	v_add_co_u32_e64 v250, s[98:99], v68, v249
	s_nop 1
	v_addc_co_u32_e64 v251, s[98:99], v69, v251, s[98:99]
	s_waitcnt lgkmcnt(0)
	global_store_dwordx4 v[250:251], v[244:247], off
	s_and_b64 vcc, exec, s[8:9]
	s_nop 0
	v_or_b32_e32 v64, s44, v147
	v_or_b32_e32 v65, s43, v147
	v_cndmask_b32_e64 v64, v64, v65, s[4:5]
	v_ashrrev_i32_e32 v65, 31, v64
	s_cbranch_vccnz .LBB0_366
	s_and_b64 s[44:45], s[4:5], exec
	s_cselect_b32 s43, s30, s34
	s_cselect_b32 s44, s29, s31
	v_mov_b32_e32 v66, s44
	v_mov_b32_e32 v67, s43
	v_lshl_add_u64 v[66:67], v[64:65], 2, v[66:67]
	global_load_dword v79, v[66:67], off
	s_and_b64 vcc, exec, s[8:9]
	s_cbranch_vccz .LBB0_367

; __device__ __forceinline__ unsigned cvt_pk_bf16(float lo, float hi) { unsigned r; asm volatile("v_cvt_pk_bf16_f32 %0, %1, %2" : "=v"(r) : "v"(lo), "v"(hi)); return r; }
;   DI void operator()(const pg8::f32x4 (&acc)[2][2][4][2], const pg8::Unit& u, int wr, int wc, int fr, int fq) const {
;     const int row0 = u.pm * 256 + wr * 64 + fr, cl = wc * 32 + 8 * fq;
;     const int kind = u.pn;
;     bfr* base = RW + (size_t)kind * MR * 256;
;     const float osc = (kind < 2) ? 0.6065306597126334f : 1.f;
; #pragma unroll
;     for (int bj = 0; bj < 2; ++bj) {
;       const int c0 = cl + bj * 128;
;       float bias[8];
; #pragma unroll
;       for (int q = 0; q < 8; ++q) bias[q] = (kind < 2) ? w0[kind * 256 + c0 + q] : ((kind < 4) ? a0[(kind - 2) * 256 + c0 + q] : 0.f);
; #pragma unroll
;       for (int ai = 0; ai < 2; ++ai)
; #pragma unroll
;         for (int m = 0; m < 4; ++m) {
;           float o[8];
; #pragma unroll
;           for (int n = 0; n < 2; ++n)
; #pragma unroll
;             for (int e = 0; e < 4; ++e) {
;               const float x = acc[ai][bj][m][n][e] + bias[n * 4 + e];
;               const float sg = osc * __builtin_amdgcn_rcpf(1.f + __expf(-x));
;               o[n * 4 + e] = (kind < 4) ? sg : x;
;             }
;           u32x4 w; w.x = pg8::cvt_pk_bf16(o[0], o[1]); w.y = pg8::cvt_pk_bf16(o[2], o[3]); w.z = pg8::cvt_pk_bf16(o[4], o[5]); w.w = pg8::cvt_pk_bf16(o[6], o[7]);
;           *(u32x4*)(base + (size_t)(row0 + ai * 128 + m * 16) * 256 + c0) = w;
;         }
;     }
;   }
.LBB0_374:
	s_waitcnt vmcnt(0)
	v_add_f32_e32 v60, v60, v79
	v_mul_f32_e32 v80, 0xbfb8aa3b, v60
	v_exp_f32_e32 v80, v80
	v_add_f32_e32 v61, v61, v77
	v_add_f32_e32 v62, v62, v78
	v_add_f32_e32 v63, v63, v75
	v_add_f32_e32 v80, 1.0, v80
	v_rcp_f32_e32 v80, v80
	v_add_f32_e32 v56, v56, v76
	v_add_f32_e32 v52, v52, v79
	v_add_f32_e32 v53, v53, v77
	v_mul_f32_e32 v80, v149, v80
	v_cndmask_b32_e64 v60, v60, v80, s[2:3]
	v_mul_f32_e32 v80, 0xbfb8aa3b, v61
	v_exp_f32_e32 v80, v80
	v_add_f32_e32 v54, v54, v78
	v_add_f32_e32 v55, v55, v75
	v_add_f32_e32 v48, v48, v76
	v_add_f32_e32 v80, 1.0, v80
	v_rcp_f32_e32 v80, v80
	v_add_f32_e32 v44, v44, v79
	v_add_f32_e32 v45, v45, v77
	v_add_f32_e32 v46, v46, v78
	v_mul_f32_e32 v80, v149, v80
	v_cndmask_b32_e64 v61, v61, v80, s[2:3]
	v_mul_f32_e32 v80, 0xbfb8aa3b, v62
	v_exp_f32_e32 v80, v80
	v_add_f32_e32 v47, v47, v75
	v_add_f32_e32 v40, v40, v76
	v_add_f32_e32 v36, v36, v79
	v_add_f32_e32 v80, 1.0, v80
	v_rcp_f32_e32 v80, v80
	v_add_f32_e32 v37, v37, v77
	v_add_f32_e32 v38, v38, v78
	v_add_f32_e32 v39, v39, v75
	v_mul_f32_e32 v80, v149, v80
	v_cndmask_b32_e64 v62, v62, v80, s[2:3]
	v_mul_f32_e32 v80, 0xbfb8aa3b, v63
	v_exp_f32_e32 v80, v80
	v_add_f32_e32 v32, v32, v76
	v_add_f32_e32 v28, v28, v79
	v_add_f32_e32 v29, v29, v77
	v_add_f32_e32 v80, 1.0, v80
	v_rcp_f32_e32 v80, v80
	v_add_f32_e32 v30, v30, v78
	v_add_f32_e32 v31, v31, v75
	v_add_f32_e32 v24, v24, v76
	v_mul_f32_e32 v80, v149, v80
	v_cndmask_b32_e64 v63, v63, v80, s[2:3]
	v_mul_f32_e32 v80, 0xbfb8aa3b, v56
	v_exp_f32_e32 v80, v80
	s_mov_b64 s[4:5], 0x10000
	v_lshl_add_u64 v[70:71], v[120:121], 0, s[4:5]
	v_add_f32_e32 v20, v20, v79
	v_add_f32_e32 v80, 1.0, v80
	v_rcp_f32_e32 v80, v80
	v_add_f32_e32 v21, v21, v77
	v_add_f32_e32 v22, v22, v78
	v_add_f32_e32 v23, v23, v75
	v_mul_f32_e32 v80, v149, v80
	v_cndmask_b32_e64 v80, v56, v80, s[2:3]
	v_add_f32_e32 v56, v57, v73
	v_mul_f32_e32 v57, 0xbfb8aa3b, v56
	v_exp_f32_e32 v57, v57
	v_add_f32_e32 v16, v16, v76
	s_mov_b64 s[4:5], 0x12000
	v_lshl_add_u64 v[68:69], v[120:121], 0, s[4:5]
	v_add_f32_e32 v57, 1.0, v57
	v_rcp_f32_e32 v57, v57
	v_add_f32_e32 v12, v12, v79
	v_add_f32_e32 v13, v13, v77
	v_add_f32_e32 v14, v14, v78
	v_mul_f32_e32 v57, v149, v57
	v_cndmask_b32_e64 v81, v56, v57, s[2:3]
	v_add_f32_e32 v56, v58, v74
	v_mul_f32_e32 v57, 0xbfb8aa3b, v56
	v_exp_f32_e32 v57, v57
	v_add_f32_e32 v15, v15, v75
	v_add_f32_e32 v8, v8, v76
	s_mov_b64 s[4:5], 0x14000
	v_add_f32_e32 v57, 1.0, v57
	v_rcp_f32_e32 v57, v57
	v_lshl_add_u64 v[66:67], v[120:121], 0, s[4:5]
	v_add_f32_e32 v4, v4, v79
	v_add_f32_e32 v5, v5, v77
	v_mul_f32_e32 v57, v149, v57
	v_cndmask_b32_e64 v82, v56, v57, s[2:3]
	v_add_f32_e32 v56, v59, v72
	v_mul_f32_e32 v57, 0xbfb8aa3b, v56
	v_exp_f32_e32 v57, v57
	v_add_f32_e32 v6, v6, v78
	v_add_f32_e32 v7, v7, v75
	v_add_f32_e32 v0, v0, v76
	v_add_f32_e32 v57, 1.0, v57
	v_rcp_f32_e32 v57, v57
	s_mov_b64 s[4:5], 0x16000
	v_lshl_add_u64 v[64:65], v[120:121], 0, s[4:5]
	s_and_b64 vcc, exec, s[6:7]
	v_mul_f32_e32 v57, v149, v57
	v_cndmask_b32_e64 v59, v56, v57, s[2:3]
	v_cvt_pk_bf16_f32 v56, v60, v61
	v_cvt_pk_bf16_f32 v57, v62, v63
	v_cvt_pk_bf16_f32 v58, v80, v81
	v_cvt_pk_bf16_f32 v59, v82, v59
	v_and_b32_e32 v250, 63, v182
	v_lshrrev_b32_e32 v251, 2, v250
	v_and_b32_e32 v248, 3, v250
	v_lshlrev_b32_e32 v249, 4, v248
	v_lshl_add_u32 v248, v248, 4, v251
	v_lshlrev_b32_e32 v248, 2, v248
	v_lshl_add_u32 v249, v251, 9, v249
	v_and_b32_e32 v251, 15, v250
	v_lshrrev_b32_e32 v250, 4, v250
	v_lshlrev_b32_e32 v251, 9, v251
	v_lshl_add_u32 v251, v250, 4, v251
	v_sub_u32_e32 v249, v249, v251
	ds_bpermute_b32 v244, v248, v56
	ds_bpermute_b32 v245, v248, v57
	ds_bpermute_b32 v246, v248, v58
	ds_bpermute_b32 v247, v248, v59
	v_ashrrev_i32_e32 v251, 31, v249
	v_add_co_u32_e64 v250, s[98:99], v120, v249
	s_nop 1
	v_addc_co_u32_e64 v251, s[98:99], v121, v251, s[98:99]
	s_waitcnt lgkmcnt(0)
	global_store_dwordx4 v[250:251], v[244:247], off offset:256
	s_nop 1
	v_mul_f32_e32 v56, 0xbfb8aa3b, v52
	v_exp_f32_e32 v56, v56
	s_nop 0
	v_add_f32_e32 v56, 1.0, v56
	v_rcp_f32_e32 v56, v56
	s_nop 0
	v_mul_f32_e32 v56, v149, v56
	v_cndmask_b32_e64 v52, v52, v56, s[2:3]
	v_mul_f32_e32 v56, 0xbfb8aa3b, v53
	v_exp_f32_e32 v56, v56
	s_nop 0
	v_add_f32_e32 v56, 1.0, v56
	v_rcp_f32_e32 v56, v56
	s_nop 0
	v_mul_f32_e32 v56, v149, v56
	v_cndmask_b32_e64 v53, v53, v56, s[2:3]
	v_mul_f32_e32 v56, 0xbfb8aa3b, v54
	v_exp_f32_e32 v56, v56
	s_nop 0
	v_add_f32_e32 v56, 1.0, v56
	v_rcp_f32_e32 v56, v56
	s_nop 0
	v_mul_f32_e32 v56, v149, v56
	v_cndmask_b32_e64 v54, v54, v56, s[2:3]
	v_mul_f32_e32 v56, 0xbfb8aa3b, v55
	v_exp_f32_e32 v56, v56
	s_nop 0
	v_add_f32_e32 v56, 1.0, v56
	v_rcp_f32_e32 v56, v56
	s_nop 0
	v_mul_f32_e32 v56, v149, v56
	v_cndmask_b32_e64 v55, v55, v56, s[2:3]
	v_mul_f32_e32 v56, 0xbfb8aa3b, v48
	v_exp_f32_e32 v56, v56
	s_nop 0
	v_add_f32_e32 v56, 1.0, v56
	v_rcp_f32_e32 v56, v56
	s_nop 0
	v_mul_f32_e32 v56, v149, v56
	v_cndmask_b32_e64 v56, v48, v56, s[2:3]
	v_add_f32_e32 v48, v49, v73
	v_mul_f32_e32 v49, 0xbfb8aa3b, v48
	v_exp_f32_e32 v49, v49
	s_nop 0
	v_add_f32_e32 v49, 1.0, v49
	v_rcp_f32_e32 v49, v49
	s_nop 0
	v_mul_f32_e32 v49, v149, v49
	v_cndmask_b32_e64 v57, v48, v49, s[2:3]
	v_add_f32_e32 v48, v50, v74
	v_mul_f32_e32 v49, 0xbfb8aa3b, v48
	v_exp_f32_e32 v49, v49
	s_nop 0
	v_add_f32_e32 v49, 1.0, v49
	v_rcp_f32_e32 v49, v49
	s_nop 0
	v_mul_f32_e32 v49, v149, v49
	v_cndmask_b32_e64 v58, v48, v49, s[2:3]
	v_add_f32_e32 v48, v51, v72
	v_mul_f32_e32 v49, 0xbfb8aa3b, v48
	v_exp_f32_e32 v49, v49
	s_nop 0
	v_add_f32_e32 v49, 1.0, v49
	v_rcp_f32_e32 v49, v49
	s_nop 0
	v_mul_f32_e32 v49, v149, v49
	v_cndmask_b32_e64 v51, v48, v49, s[2:3]
	v_cvt_pk_bf16_f32 v48, v52, v53
	v_cvt_pk_bf16_f32 v49, v54, v55
	v_cvt_pk_bf16_f32 v50, v56, v57
	v_cvt_pk_bf16_f32 v51, v58, v51
	v_and_b32_e32 v250, 63, v182
	v_lshrrev_b32_e32 v251, 2, v250
	v_and_b32_e32 v248, 3, v250
	v_lshlrev_b32_e32 v249, 4, v248
	v_lshl_add_u32 v248, v248, 4, v251
	v_lshlrev_b32_e32 v248, 2, v248
	v_lshl_add_u32 v249, v251, 9, v249
	v_and_b32_e32 v251, 15, v250
	v_lshrrev_b32_e32 v250, 4, v250
	v_lshlrev_b32_e32 v251, 9, v251
	v_lshl_add_u32 v251, v250, 4, v251
	v_sub_u32_e32 v249, v249, v251
	ds_bpermute_b32 v244, v248, v48
	ds_bpermute_b32 v245, v248, v49
	ds_bpermute_b32 v246, v248, v50
	ds_bpermute_b32 v247, v248, v51
	v_ashrrev_i32_e32 v251, 31, v249
	v_add_co_u32_e64 v250, s[98:99], v112, v249
	s_nop 1
	v_addc_co_u32_e64 v251, s[98:99], v113, v251, s[98:99]
	s_waitcnt lgkmcnt(0)
; __device__ __forceinline__ unsigned cvt_pk_bf16(float lo, float hi) { unsigned r; asm volatile("v_cvt_pk_bf16_f32 %0, %1, %2" : "=v"(r) : "v"(lo), "v"(hi)); return r; }
;   DI void operator()(const pg8::f32x4 (&acc)[2][2][4][2], const pg8::Unit& u, int wr, int wc, int fr, int fq) const {
;     const int row0 = u.pm * 256 + wr * 64 + fr, cl = wc * 32 + 8 * fq;
;     const int kind = u.pn;
;     bfr* base = RW + (size_t)kind * MR * 256;
;     const float osc = (kind < 2) ? 0.6065306597126334f : 1.f;
; #pragma unroll
;     for (int bj = 0; bj < 2; ++bj) {
;       const int c0 = cl + bj * 128;
;       float bias[8];
; #pragma unroll
;       for (int q = 0; q < 8; ++q) bias[q] = (kind < 2) ? w0[kind * 256 + c0 + q] : ((kind < 4) ? a0[(kind - 2) * 256 + c0 + q] : 0.f);
; #pragma unroll
;       for (int ai = 0; ai < 2; ++ai)
; #pragma unroll
;         for (int m = 0; m < 4; ++m) {
;           float o[8];
; #pragma unroll
;           for (int n = 0; n < 2; ++n)
; #pragma unroll
;             for (int e = 0; e < 4; ++e) {
;               const float x = acc[ai][bj][m][n][e] + bias[n * 4 + e];
;               const float sg = osc * __builtin_amdgcn_rcpf(1.f + __expf(-x));
;               o[n * 4 + e] = (kind < 4) ? sg : x;
;             }
;           u32x4 w; w.x = pg8::cvt_pk_bf16(o[0], o[1]); w.y = pg8::cvt_pk_bf16(o[2], o[3]); w.z = pg8::cvt_pk_bf16(o[4], o[5]); w.w = pg8::cvt_pk_bf16(o[6], o[7]);
;           *(u32x4*)(base + (size_t)(row0 + ai * 128 + m * 16) * 256 + c0) = w;
;         }
;     }
;   }
	global_store_dwordx4 v[250:251], v[244:247], off offset:256
	s_nop 1
	v_mul_f32_e32 v48, 0xbfb8aa3b, v44
	v_exp_f32_e32 v48, v48
	s_nop 0
	v_add_f32_e32 v48, 1.0, v48
	v_rcp_f32_e32 v48, v48
	s_nop 0
	v_mul_f32_e32 v48, v149, v48
	v_cndmask_b32_e64 v44, v44, v48, s[2:3]
	v_mul_f32_e32 v48, 0xbfb8aa3b, v45
	v_exp_f32_e32 v48, v48
	s_nop 0
	v_add_f32_e32 v48, 1.0, v48
	v_rcp_f32_e32 v48, v48
	s_nop 0
	v_mul_f32_e32 v48, v149, v48
	v_cndmask_b32_e64 v45, v45, v48, s[2:3]
	v_mul_f32_e32 v48, 0xbfb8aa3b, v46
	v_exp_f32_e32 v48, v48
	s_nop 0
	v_add_f32_e32 v48, 1.0, v48
	v_rcp_f32_e32 v48, v48
	s_nop 0
	v_mul_f32_e32 v48, v149, v48
	v_cndmask_b32_e64 v46, v46, v48, s[2:3]
	v_mul_f32_e32 v48, 0xbfb8aa3b, v47
	v_exp_f32_e32 v48, v48
	s_nop 0
	v_add_f32_e32 v48, 1.0, v48
	v_rcp_f32_e32 v48, v48
	s_nop 0
	v_mul_f32_e32 v48, v149, v48
	v_cndmask_b32_e64 v47, v47, v48, s[2:3]
	v_mul_f32_e32 v48, 0xbfb8aa3b, v40
	v_exp_f32_e32 v48, v48
	s_nop 0
	v_add_f32_e32 v48, 1.0, v48
	v_rcp_f32_e32 v48, v48
	s_nop 0
	v_mul_f32_e32 v48, v149, v48
	v_cndmask_b32_e64 v48, v40, v48, s[2:3]
	v_add_f32_e32 v40, v41, v73
	v_mul_f32_e32 v41, 0xbfb8aa3b, v40
	v_exp_f32_e32 v41, v41
	s_nop 0
	v_add_f32_e32 v41, 1.0, v41
	v_rcp_f32_e32 v41, v41
	s_nop 0
	v_mul_f32_e32 v41, v149, v41
	v_cndmask_b32_e64 v49, v40, v41, s[2:3]
	v_add_f32_e32 v40, v42, v74
	v_mul_f32_e32 v41, 0xbfb8aa3b, v40
	v_exp_f32_e32 v41, v41
	s_nop 0
	v_add_f32_e32 v41, 1.0, v41
	v_rcp_f32_e32 v41, v41
	s_nop 0
	v_mul_f32_e32 v41, v149, v41
	v_cndmask_b32_e64 v50, v40, v41, s[2:3]
	v_add_f32_e32 v40, v43, v72
	v_mul_f32_e32 v41, 0xbfb8aa3b, v40
	v_exp_f32_e32 v41, v41
	s_nop 0
	v_add_f32_e32 v41, 1.0, v41
	v_rcp_f32_e32 v41, v41
	s_nop 0
	v_mul_f32_e32 v41, v149, v41
	v_cndmask_b32_e64 v43, v40, v41, s[2:3]
	v_cvt_pk_bf16_f32 v40, v44, v45
	v_cvt_pk_bf16_f32 v41, v46, v47
	v_cvt_pk_bf16_f32 v42, v48, v49
	v_cvt_pk_bf16_f32 v43, v50, v43
	v_and_b32_e32 v250, 63, v182
	v_lshrrev_b32_e32 v251, 2, v250
	v_and_b32_e32 v248, 3, v250
	v_lshlrev_b32_e32 v249, 4, v248
	v_lshl_add_u32 v248, v248, 4, v251
	v_lshlrev_b32_e32 v248, 2, v248
	v_lshl_add_u32 v249, v251, 9, v249
	v_and_b32_e32 v251, 15, v250
	v_lshrrev_b32_e32 v250, 4, v250
	v_lshlrev_b32_e32 v251, 9, v251
	v_lshl_add_u32 v251, v250, 4, v251
	v_sub_u32_e32 v249, v249, v251
	ds_bpermute_b32 v244, v248, v40
	ds_bpermute_b32 v245, v248, v41
	ds_bpermute_b32 v246, v248, v42
	ds_bpermute_b32 v247, v248, v43
	v_ashrrev_i32_e32 v251, 31, v249
	v_add_co_u32_e64 v250, s[98:99], v104, v249
	s_nop 1
	v_addc_co_u32_e64 v251, s[98:99], v105, v251, s[98:99]
	s_waitcnt lgkmcnt(0)
	global_store_dwordx4 v[250:251], v[244:247], off offset:256
	s_nop 1
	v_mul_f32_e32 v40, 0xbfb8aa3b, v36
	v_exp_f32_e32 v40, v40
	s_nop 0
	v_add_f32_e32 v40, 1.0, v40
	v_rcp_f32_e32 v40, v40
	s_nop 0
	v_mul_f32_e32 v40, v149, v40
	v_cndmask_b32_e64 v36, v36, v40, s[2:3]
	v_mul_f32_e32 v40, 0xbfb8aa3b, v37
	v_exp_f32_e32 v40, v40
	s_nop 0
	v_add_f32_e32 v40, 1.0, v40
	v_rcp_f32_e32 v40, v40
	s_nop 0
	v_mul_f32_e32 v40, v149, v40
	v_cndmask_b32_e64 v37, v37, v40, s[2:3]
	v_mul_f32_e32 v40, 0xbfb8aa3b, v38
	v_exp_f32_e32 v40, v40
	s_nop 0
	v_add_f32_e32 v40, 1.0, v40
	v_rcp_f32_e32 v40, v40
	s_nop 0
	v_mul_f32_e32 v40, v149, v40
	v_cndmask_b32_e64 v38, v38, v40, s[2:3]
	v_mul_f32_e32 v40, 0xbfb8aa3b, v39
	v_exp_f32_e32 v40, v40
	s_nop 0
	v_add_f32_e32 v40, 1.0, v40
	v_rcp_f32_e32 v40, v40
	s_nop 0
	v_mul_f32_e32 v40, v149, v40
	v_cndmask_b32_e64 v39, v39, v40, s[2:3]
	v_mul_f32_e32 v40, 0xbfb8aa3b, v32
	v_exp_f32_e32 v40, v40
	s_nop 0
	v_add_f32_e32 v40, 1.0, v40
	v_rcp_f32_e32 v40, v40
	s_nop 0
	v_mul_f32_e32 v40, v149, v40
	v_cndmask_b32_e64 v40, v32, v40, s[2:3]
	v_add_f32_e32 v32, v33, v73
	v_mul_f32_e32 v33, 0xbfb8aa3b, v32
	v_exp_f32_e32 v33, v33
	s_nop 0
	v_add_f32_e32 v33, 1.0, v33
	v_rcp_f32_e32 v33, v33
	s_nop 0
	v_mul_f32_e32 v33, v149, v33
	v_cndmask_b32_e64 v41, v32, v33, s[2:3]
	v_add_f32_e32 v32, v34, v74
	v_mul_f32_e32 v33, 0xbfb8aa3b, v32
	v_exp_f32_e32 v33, v33
	s_nop 0
	v_add_f32_e32 v33, 1.0, v33
	v_rcp_f32_e32 v33, v33
	s_nop 0
	v_mul_f32_e32 v33, v149, v33
	v_cndmask_b32_e64 v42, v32, v33, s[2:3]
	v_add_f32_e32 v32, v35, v72
	v_mul_f32_e32 v33, 0xbfb8aa3b, v32
	v_exp_f32_e32 v33, v33
	s_nop 0
	v_add_f32_e32 v33, 1.0, v33
	v_rcp_f32_e32 v33, v33
	s_nop 0
	v_mul_f32_e32 v33, v149, v33
	v_cndmask_b32_e64 v35, v32, v33, s[2:3]
	v_cvt_pk_bf16_f32 v32, v36, v37
	v_cvt_pk_bf16_f32 v33, v38, v39
	v_cvt_pk_bf16_f32 v34, v40, v41
	v_cvt_pk_bf16_f32 v35, v42, v35
	v_and_b32_e32 v250, 63, v182
	v_lshrrev_b32_e32 v251, 2, v250
	v_and_b32_e32 v248, 3, v250
	v_lshlrev_b32_e32 v249, 4, v248
	v_lshl_add_u32 v248, v248, 4, v251
	v_lshlrev_b32_e32 v248, 2, v248
	v_lshl_add_u32 v249, v251, 9, v249
	v_and_b32_e32 v251, 15, v250
	v_lshrrev_b32_e32 v250, 4, v250
	v_lshlrev_b32_e32 v251, 9, v251
	v_lshl_add_u32 v251, v250, 4, v251
	v_sub_u32_e32 v249, v249, v251
	ds_bpermute_b32 v244, v248, v32
	ds_bpermute_b32 v245, v248, v33
	ds_bpermute_b32 v246, v248, v34
	ds_bpermute_b32 v247, v248, v35
	v_ashrrev_i32_e32 v251, 31, v249
	v_add_co_u32_e64 v250, s[98:99], v96, v249
	s_nop 1
	v_addc_co_u32_e64 v251, s[98:99], v97, v251, s[98:99]
	s_waitcnt lgkmcnt(0)
; __device__ __forceinline__ unsigned cvt_pk_bf16(float lo, float hi) { unsigned r; asm volatile("v_cvt_pk_bf16_f32 %0, %1, %2" : "=v"(r) : "v"(lo), "v"(hi)); return r; }
;   DI void operator()(const pg8::f32x4 (&acc)[2][2][4][2], const pg8::Unit& u, int wr, int wc, int fr, int fq) const {
;     const int row0 = u.pm * 256 + wr * 64 + fr, cl = wc * 32 + 8 * fq;
;     const int kind = u.pn;
;     bfr* base = RW + (size_t)kind * MR * 256;
;     const float osc = (kind < 2) ? 0.6065306597126334f : 1.f;
; #pragma unroll
;     for (int bj = 0; bj < 2; ++bj) {
;       const int c0 = cl + bj * 128;
;       float bias[8];
; #pragma unroll
;       for (int q = 0; q < 8; ++q) bias[q] = (kind < 2) ? w0[kind * 256 + c0 + q] : ((kind < 4) ? a0[(kind - 2) * 256 + c0 + q] : 0.f);
; #pragma unroll
;       for (int ai = 0; ai < 2; ++ai)
; #pragma unroll
;         for (int m = 0; m < 4; ++m) {
;           float o[8];
; #pragma unroll
;           for (int n = 0; n < 2; ++n)
; #pragma unroll
;             for (int e = 0; e < 4; ++e) {
;               const float x = acc[ai][bj][m][n][e] + bias[n * 4 + e];
;               const float sg = osc * __builtin_amdgcn_rcpf(1.f + __expf(-x));
;               o[n * 4 + e] = (kind < 4) ? sg : x;
;             }
;           u32x4 w; w.x = pg8::cvt_pk_bf16(o[0], o[1]); w.y = pg8::cvt_pk_bf16(o[2], o[3]); w.z = pg8::cvt_pk_bf16(o[4], o[5]); w.w = pg8::cvt_pk_bf16(o[6], o[7]);
;           *(u32x4*)(base + (size_t)(row0 + ai * 128 + m * 16) * 256 + c0) = w;
;         }
;     }
;   }
	global_store_dwordx4 v[250:251], v[244:247], off offset:256
	s_nop 1
	v_mul_f32_e32 v32, 0xbfb8aa3b, v28
	v_exp_f32_e32 v32, v32
	s_nop 0
	v_add_f32_e32 v32, 1.0, v32
	v_rcp_f32_e32 v32, v32
	s_nop 0
	v_mul_f32_e32 v32, v149, v32
	v_cndmask_b32_e64 v28, v28, v32, s[2:3]
	v_mul_f32_e32 v32, 0xbfb8aa3b, v29
	v_exp_f32_e32 v32, v32
	s_nop 0
	v_add_f32_e32 v32, 1.0, v32
	v_rcp_f32_e32 v32, v32
	s_nop 0
	v_mul_f32_e32 v32, v149, v32
	v_cndmask_b32_e64 v29, v29, v32, s[2:3]
	v_mul_f32_e32 v32, 0xbfb8aa3b, v30
	v_exp_f32_e32 v32, v32
	s_nop 0
	v_add_f32_e32 v32, 1.0, v32
	v_rcp_f32_e32 v32, v32
	s_nop 0
	v_mul_f32_e32 v32, v149, v32
	v_cndmask_b32_e64 v30, v30, v32, s[2:3]
	v_mul_f32_e32 v32, 0xbfb8aa3b, v31
	v_exp_f32_e32 v32, v32
	s_nop 0
	v_add_f32_e32 v32, 1.0, v32
	v_rcp_f32_e32 v32, v32
	s_nop 0
	v_mul_f32_e32 v32, v149, v32
	v_cndmask_b32_e64 v31, v31, v32, s[2:3]
	v_mul_f32_e32 v32, 0xbfb8aa3b, v24
	v_exp_f32_e32 v32, v32
	s_nop 0
	v_add_f32_e32 v32, 1.0, v32
	v_rcp_f32_e32 v32, v32
	s_nop 0
	v_mul_f32_e32 v32, v149, v32
	v_cndmask_b32_e64 v32, v24, v32, s[2:3]
	v_add_f32_e32 v24, v25, v73
	v_mul_f32_e32 v25, 0xbfb8aa3b, v24
	v_exp_f32_e32 v25, v25
	s_nop 0
	v_add_f32_e32 v25, 1.0, v25
	v_rcp_f32_e32 v25, v25
	s_nop 0
	v_mul_f32_e32 v25, v149, v25
	v_cndmask_b32_e64 v33, v24, v25, s[2:3]
	v_add_f32_e32 v24, v26, v74
	v_mul_f32_e32 v25, 0xbfb8aa3b, v24
	v_exp_f32_e32 v25, v25
	s_nop 0
	v_add_f32_e32 v25, 1.0, v25
	v_rcp_f32_e32 v25, v25
	s_nop 0
	v_mul_f32_e32 v25, v149, v25
	v_cndmask_b32_e64 v34, v24, v25, s[2:3]
	v_add_f32_e32 v24, v27, v72
	v_mul_f32_e32 v25, 0xbfb8aa3b, v24
	v_exp_f32_e32 v25, v25
	s_nop 0
	v_add_f32_e32 v25, 1.0, v25
	v_rcp_f32_e32 v25, v25
	s_nop 0
	v_mul_f32_e32 v25, v149, v25
	v_cndmask_b32_e64 v27, v24, v25, s[2:3]
	v_cvt_pk_bf16_f32 v24, v28, v29
	v_cvt_pk_bf16_f32 v25, v30, v31
	v_cvt_pk_bf16_f32 v26, v32, v33
	v_cvt_pk_bf16_f32 v27, v34, v27
	v_and_b32_e32 v250, 63, v182
	v_lshrrev_b32_e32 v251, 2, v250
	v_and_b32_e32 v248, 3, v250
	v_lshlrev_b32_e32 v249, 4, v248
	v_lshl_add_u32 v248, v248, 4, v251
	v_lshlrev_b32_e32 v248, 2, v248
	v_lshl_add_u32 v249, v251, 9, v249
	v_and_b32_e32 v251, 15, v250
	v_lshrrev_b32_e32 v250, 4, v250
	v_lshlrev_b32_e32 v251, 9, v251
	v_lshl_add_u32 v251, v250, 4, v251
	v_sub_u32_e32 v249, v249, v251
	ds_bpermute_b32 v244, v248, v24
	ds_bpermute_b32 v245, v248, v25
	ds_bpermute_b32 v246, v248, v26
	ds_bpermute_b32 v247, v248, v27
	v_ashrrev_i32_e32 v251, 31, v249
	v_add_co_u32_e64 v250, s[98:99], v70, v249
	s_nop 1
	v_addc_co_u32_e64 v251, s[98:99], v71, v251, s[98:99]
	s_waitcnt lgkmcnt(0)
	global_store_dwordx4 v[250:251], v[244:247], off offset:256
	s_nop 1
	v_mul_f32_e32 v24, 0xbfb8aa3b, v20
	v_exp_f32_e32 v24, v24
	s_nop 0
	v_add_f32_e32 v24, 1.0, v24
	v_rcp_f32_e32 v24, v24
	s_nop 0
	v_mul_f32_e32 v24, v149, v24
	v_cndmask_b32_e64 v20, v20, v24, s[2:3]
	v_mul_f32_e32 v24, 0xbfb8aa3b, v21
	v_exp_f32_e32 v24, v24
	s_nop 0
	v_add_f32_e32 v24, 1.0, v24
	v_rcp_f32_e32 v24, v24
	s_nop 0
	v_mul_f32_e32 v24, v149, v24
	v_cndmask_b32_e64 v21, v21, v24, s[2:3]
	v_mul_f32_e32 v24, 0xbfb8aa3b, v22
	v_exp_f32_e32 v24, v24
	s_nop 0
	v_add_f32_e32 v24, 1.0, v24
	v_rcp_f32_e32 v24, v24
	s_nop 0
	v_mul_f32_e32 v24, v149, v24
	v_cndmask_b32_e64 v22, v22, v24, s[2:3]
	v_mul_f32_e32 v24, 0xbfb8aa3b, v23
	v_exp_f32_e32 v24, v24
	s_nop 0
	v_add_f32_e32 v24, 1.0, v24
	v_rcp_f32_e32 v24, v24
	s_nop 0
	v_mul_f32_e32 v24, v149, v24
	v_cndmask_b32_e64 v23, v23, v24, s[2:3]
	v_mul_f32_e32 v24, 0xbfb8aa3b, v16
	v_exp_f32_e32 v24, v24
	s_nop 0
	v_add_f32_e32 v24, 1.0, v24
	v_rcp_f32_e32 v24, v24
	s_nop 0
	v_mul_f32_e32 v24, v149, v24
	v_cndmask_b32_e64 v24, v16, v24, s[2:3]
	v_add_f32_e32 v16, v17, v73
	v_mul_f32_e32 v17, 0xbfb8aa3b, v16
	v_exp_f32_e32 v17, v17
	s_nop 0
	v_add_f32_e32 v17, 1.0, v17
	v_rcp_f32_e32 v17, v17
	s_nop 0
	v_mul_f32_e32 v17, v149, v17
	v_cndmask_b32_e64 v25, v16, v17, s[2:3]
	v_add_f32_e32 v16, v18, v74
	v_mul_f32_e32 v17, 0xbfb8aa3b, v16
	v_exp_f32_e32 v17, v17
	s_nop 0
	v_add_f32_e32 v17, 1.0, v17
	v_rcp_f32_e32 v17, v17
	s_nop 0
	v_mul_f32_e32 v17, v149, v17
	v_cndmask_b32_e64 v26, v16, v17, s[2:3]
	v_add_f32_e32 v16, v19, v72
	v_mul_f32_e32 v17, 0xbfb8aa3b, v16
	v_exp_f32_e32 v17, v17
	s_nop 0
	v_add_f32_e32 v17, 1.0, v17
	v_rcp_f32_e32 v17, v17
	s_nop 0
	v_mul_f32_e32 v17, v149, v17
	v_cndmask_b32_e64 v19, v16, v17, s[2:3]
	v_cvt_pk_bf16_f32 v16, v20, v21
	v_cvt_pk_bf16_f32 v17, v22, v23
	v_cvt_pk_bf16_f32 v18, v24, v25
	v_cvt_pk_bf16_f32 v19, v26, v19
	v_and_b32_e32 v250, 63, v182
	v_lshrrev_b32_e32 v251, 2, v250
	v_and_b32_e32 v248, 3, v250
	v_lshlrev_b32_e32 v249, 4, v248
	v_lshl_add_u32 v248, v248, 4, v251
	v_lshlrev_b32_e32 v248, 2, v248
	v_lshl_add_u32 v249, v251, 9, v249
	v_and_b32_e32 v251, 15, v250
	v_lshrrev_b32_e32 v250, 4, v250
	v_lshlrev_b32_e32 v251, 9, v251
	v_lshl_add_u32 v251, v250, 4, v251
	v_sub_u32_e32 v249, v249, v251
	ds_bpermute_b32 v244, v248, v16
	ds_bpermute_b32 v245, v248, v17
	ds_bpermute_b32 v246, v248, v18
	ds_bpermute_b32 v247, v248, v19
	v_ashrrev_i32_e32 v251, 31, v249
	v_add_co_u32_e64 v250, s[98:99], v68, v249
	s_nop 1
	v_addc_co_u32_e64 v251, s[98:99], v69, v251, s[98:99]
	s_waitcnt lgkmcnt(0)
; __device__ __forceinline__ unsigned cvt_pk_bf16(float lo, float hi) { unsigned r; asm volatile("v_cvt_pk_bf16_f32 %0, %1, %2" : "=v"(r) : "v"(lo), "v"(hi)); return r; }
;   DI void operator()(const pg8::f32x4 (&acc)[2][2][4][2], const pg8::Unit& u, int wr, int wc, int fr, int fq) const {
;     const int row0 = u.pm * 256 + wr * 64 + fr, cl = wc * 32 + 8 * fq;
;     const int kind = u.pn;
;     bfr* base = RW + (size_t)kind * MR * 256;
;     const float osc = (kind < 2) ? 0.6065306597126334f : 1.f;
; #pragma unroll
;     for (int bj = 0; bj < 2; ++bj) {
;       const int c0 = cl + bj * 128;
;       float bias[8];
; #pragma unroll
;       for (int q = 0; q < 8; ++q) bias[q] = (kind < 2) ? w0[kind * 256 + c0 + q] : ((kind < 4) ? a0[(kind - 2) * 256 + c0 + q] : 0.f);
; #pragma unroll
;       for (int ai = 0; ai < 2; ++ai)
; #pragma unroll
;         for (int m = 0; m < 4; ++m) {
;           float o[8];
; #pragma unroll
;           for (int n = 0; n < 2; ++n)
; #pragma unroll
;             for (int e = 0; e < 4; ++e) {
;               const float x = acc[ai][bj][m][n][e] + bias[n * 4 + e];
;               const float sg = osc * __builtin_amdgcn_rcpf(1.f + __expf(-x));
;               o[n * 4 + e] = (kind < 4) ? sg : x;
;             }
;           u32x4 w; w.x = pg8::cvt_pk_bf16(o[0], o[1]); w.y = pg8::cvt_pk_bf16(o[2], o[3]); w.z = pg8::cvt_pk_bf16(o[4], o[5]); w.w = pg8::cvt_pk_bf16(o[6], o[7]);
;           *(u32x4*)(base + (size_t)(row0 + ai * 128 + m * 16) * 256 + c0) = w;
;         }
;     }
;   }
	global_store_dwordx4 v[250:251], v[244:247], off offset:256
	s_nop 1
	v_mul_f32_e32 v16, 0xbfb8aa3b, v12
	v_exp_f32_e32 v16, v16
	s_nop 0
	v_add_f32_e32 v16, 1.0, v16
	v_rcp_f32_e32 v16, v16
	s_nop 0
	v_mul_f32_e32 v16, v149, v16
	v_cndmask_b32_e64 v12, v12, v16, s[2:3]
	v_mul_f32_e32 v16, 0xbfb8aa3b, v13
	v_exp_f32_e32 v16, v16
	s_nop 0
	v_add_f32_e32 v16, 1.0, v16
	v_rcp_f32_e32 v16, v16
	s_nop 0
	v_mul_f32_e32 v16, v149, v16
	v_cndmask_b32_e64 v13, v13, v16, s[2:3]
	v_mul_f32_e32 v16, 0xbfb8aa3b, v14
	v_exp_f32_e32 v16, v16
	s_nop 0
	v_add_f32_e32 v16, 1.0, v16
	v_rcp_f32_e32 v16, v16
	s_nop 0
	v_mul_f32_e32 v16, v149, v16
	v_cndmask_b32_e64 v14, v14, v16, s[2:3]
	v_mul_f32_e32 v16, 0xbfb8aa3b, v15
	v_exp_f32_e32 v16, v16
	s_nop 0
	v_add_f32_e32 v16, 1.0, v16
	v_rcp_f32_e32 v16, v16
	s_nop 0
	v_mul_f32_e32 v16, v149, v16
	v_cndmask_b32_e64 v15, v15, v16, s[2:3]
	v_mul_f32_e32 v16, 0xbfb8aa3b, v8
	v_exp_f32_e32 v16, v16
	s_nop 0
	v_add_f32_e32 v16, 1.0, v16
	v_rcp_f32_e32 v16, v16
	s_nop 0
	v_mul_f32_e32 v16, v149, v16
	v_cndmask_b32_e64 v16, v8, v16, s[2:3]
	v_add_f32_e32 v8, v9, v73
	v_mul_f32_e32 v9, 0xbfb8aa3b, v8
	v_exp_f32_e32 v9, v9
	s_nop 0
	v_add_f32_e32 v9, 1.0, v9
	v_rcp_f32_e32 v9, v9
	s_nop 0
	v_mul_f32_e32 v9, v149, v9
	v_cndmask_b32_e64 v17, v8, v9, s[2:3]
	v_add_f32_e32 v8, v10, v74
	v_mul_f32_e32 v9, 0xbfb8aa3b, v8
	v_exp_f32_e32 v9, v9
	s_nop 0
	v_add_f32_e32 v9, 1.0, v9
	v_rcp_f32_e32 v9, v9
	s_nop 0
	v_mul_f32_e32 v9, v149, v9
	v_cndmask_b32_e64 v18, v8, v9, s[2:3]
	v_add_f32_e32 v8, v11, v72
	v_mul_f32_e32 v9, 0xbfb8aa3b, v8
	v_exp_f32_e32 v9, v9
	s_nop 0
	v_add_f32_e32 v9, 1.0, v9
	v_rcp_f32_e32 v9, v9
	s_nop 0
	v_mul_f32_e32 v9, v149, v9
	v_cndmask_b32_e64 v11, v8, v9, s[2:3]
	v_cvt_pk_bf16_f32 v8, v12, v13
	v_cvt_pk_bf16_f32 v9, v14, v15
	v_cvt_pk_bf16_f32 v10, v16, v17
	v_cvt_pk_bf16_f32 v11, v18, v11
	v_and_b32_e32 v250, 63, v182
	v_lshrrev_b32_e32 v251, 2, v250
	v_and_b32_e32 v248, 3, v250
	v_lshlrev_b32_e32 v249, 4, v248
	v_lshl_add_u32 v248, v248, 4, v251
	v_lshlrev_b32_e32 v248, 2, v248
	v_lshl_add_u32 v249, v251, 9, v249
	v_and_b32_e32 v251, 15, v250
	v_lshrrev_b32_e32 v250, 4, v250
	v_lshlrev_b32_e32 v251, 9, v251
	v_lshl_add_u32 v251, v250, 4, v251
	v_sub_u32_e32 v249, v249, v251
	ds_bpermute_b32 v244, v248, v8
	ds_bpermute_b32 v245, v248, v9
	ds_bpermute_b32 v246, v248, v10
	ds_bpermute_b32 v247, v248, v11
	v_ashrrev_i32_e32 v251, 31, v249
	v_add_co_u32_e64 v250, s[98:99], v66, v249
	s_nop 1
	v_addc_co_u32_e64 v251, s[98:99], v67, v251, s[98:99]
	s_waitcnt lgkmcnt(0)
	global_store_dwordx4 v[250:251], v[244:247], off offset:256
	s_nop 1
	v_mul_f32_e32 v8, 0xbfb8aa3b, v4
	v_exp_f32_e32 v8, v8
	s_nop 0
	v_add_f32_e32 v8, 1.0, v8
	v_rcp_f32_e32 v8, v8
	s_nop 0
	v_mul_f32_e32 v8, v149, v8
	v_cndmask_b32_e64 v4, v4, v8, s[2:3]
	v_mul_f32_e32 v8, 0xbfb8aa3b, v5
	v_exp_f32_e32 v8, v8
	s_nop 0
	v_add_f32_e32 v8, 1.0, v8
	v_rcp_f32_e32 v8, v8
	s_nop 0
	v_mul_f32_e32 v8, v149, v8
	v_cndmask_b32_e64 v5, v5, v8, s[2:3]
	v_mul_f32_e32 v8, 0xbfb8aa3b, v6
	v_exp_f32_e32 v8, v8
	s_nop 0
	v_add_f32_e32 v8, 1.0, v8
	v_rcp_f32_e32 v8, v8
	s_nop 0
	v_mul_f32_e32 v8, v149, v8
	v_cndmask_b32_e64 v6, v6, v8, s[2:3]
	v_mul_f32_e32 v8, 0xbfb8aa3b, v7
	v_exp_f32_e32 v8, v8
	s_nop 0
	v_add_f32_e32 v8, 1.0, v8
	v_rcp_f32_e32 v8, v8
	s_nop 0
	v_mul_f32_e32 v8, v149, v8
	v_cndmask_b32_e64 v7, v7, v8, s[2:3]
	v_mul_f32_e32 v8, 0xbfb8aa3b, v0
	v_exp_f32_e32 v8, v8
	s_nop 0
	v_add_f32_e32 v8, 1.0, v8
	v_rcp_f32_e32 v8, v8
	s_nop 0
	v_mul_f32_e32 v8, v149, v8
	v_cndmask_b32_e64 v8, v0, v8, s[2:3]
	v_add_f32_e32 v0, v1, v73
	v_mul_f32_e32 v1, 0xbfb8aa3b, v0
	v_exp_f32_e32 v1, v1
	s_nop 0
	v_add_f32_e32 v1, 1.0, v1
	v_rcp_f32_e32 v1, v1
	s_nop 0
	v_mul_f32_e32 v1, v149, v1
	v_cndmask_b32_e64 v9, v0, v1, s[2:3]
	v_add_f32_e32 v0, v2, v74
	v_mul_f32_e32 v1, 0xbfb8aa3b, v0
	v_exp_f32_e32 v1, v1
	s_nop 0
	v_add_f32_e32 v1, 1.0, v1
	v_rcp_f32_e32 v1, v1
	s_nop 0
	v_mul_f32_e32 v1, v149, v1
	v_cndmask_b32_e64 v10, v0, v1, s[2:3]
	v_add_f32_e32 v0, v3, v72
	v_mul_f32_e32 v1, 0xbfb8aa3b, v0
	v_exp_f32_e32 v1, v1
	s_nop 0
	v_add_f32_e32 v1, 1.0, v1
	v_rcp_f32_e32 v1, v1
	s_nop 0
	v_mul_f32_e32 v1, v149, v1
	v_cndmask_b32_e64 v3, v0, v1, s[2:3]
	s_mov_b64 s[2:3], -1
	v_cvt_pk_bf16_f32 v0, v4, v5
	v_cvt_pk_bf16_f32 v1, v6, v7
	v_cvt_pk_bf16_f32 v2, v8, v9
	v_cvt_pk_bf16_f32 v3, v10, v3
	v_and_b32_e32 v250, 63, v182
	v_lshrrev_b32_e32 v251, 2, v250
	v_and_b32_e32 v248, 3, v250
	v_lshlrev_b32_e32 v249, 4, v248
	v_lshl_add_u32 v248, v248, 4, v251
	v_lshlrev_b32_e32 v248, 2, v248
	v_lshl_add_u32 v249, v251, 9, v249
	v_and_b32_e32 v251, 15, v250
	v_lshrrev_b32_e32 v250, 4, v250
	v_lshlrev_b32_e32 v251, 9, v251
	v_lshl_add_u32 v251, v250, 4, v251
	v_sub_u32_e32 v249, v249, v251
	ds_bpermute_b32 v244, v248, v0
	ds_bpermute_b32 v245, v248, v1
	ds_bpermute_b32 v246, v248, v2
	ds_bpermute_b32 v247, v248, v3
	v_ashrrev_i32_e32 v251, 31, v249
	v_add_co_u32_e64 v250, s[98:99], v64, v249
	s_nop 1
	v_addc_co_u32_e64 v251, s[98:99], v65, v251, s[98:99]
	s_waitcnt lgkmcnt(0)
	global_store_dwordx4 v[250:251], v[244:247], off offset:256
	s_cbranch_vccnz .LBB0_329
	s_andn2_b64 vcc, exec, s[14:15]
	s_cbranch_vccnz .LBB0_328
	s_barrier
	s_branch .LBB0_328
